# gate stores nt sc1 + rows-phase row loads nt + no entry grid.sync
# speedup vs baseline: 1.0150x; 1.0150x over previous
; __device__ __forceinline__ float wave_sum(float v) {
;     v += __int_as_float(__builtin_amdgcn_update_dpp(0, __float_as_int(v), 0xB1, 0xf, 0xf, true));
;     v += __int_as_float(__builtin_amdgcn_update_dpp(0, __float_as_int(v), 0x4E, 0xf, 0xf, true));
;     v += __int_as_float(__builtin_amdgcn_update_dpp(0, __float_as_int(v), 0x141, 0xf, 0xf, true));
;     v += __int_as_float(__builtin_amdgcn_update_dpp(0, __float_as_int(v), 0x140, 0xf, 0xf, true));
;     const int iv = __float_as_int(v);
;     const float r0 = __int_as_float(__builtin_amdgcn_readlane(iv, 0)), r1 = __int_as_float(__builtin_amdgcn_readlane(iv, 16)), r2 = __int_as_float(__builtin_amdgcn_readlane(iv, 32)), r3 = __int_as_float(__builtin_amdgcn_readlane(iv, 48));
;     return (r0 + r1) + (r2 + r3);
; }
; __device__ __forceinline__ void phase_rows(const Ctx& c, int l) {
;     ...
;     for (int m0 = gw; m0 < MTOK; m0 += 2 * NGW) {
;         f32x4 v[2][4];
; #pragma unroll
;         for (int q = 0; q < 2; ++q) { const int mr = min(m0 + q * NGW, MTOK - 1); const f32x4* xr = (const f32x4*)(src + (size_t)mr * DM) + lane;
; #pragma unroll
;             for (int j = 0; j < 4; ++j) v[q][j] = xr[64 * j]; }
; #pragma unroll
;         for (int q = 0; q < 2; ++q) {
;         const int m = m0 + q * NGW;
;         if (m >= MTOK) continue;
;         if (l > 0) {
;             float s = 0.f;
; #pragma unroll
;             for (int j = 0; j < 4; ++j) s += (v[q][j].x + v[q][j].y) + (v[q][j].z + v[q][j].w);
;             const float mean = wave_sum(s) * (1.f / DM); float s2 = 0.f;
; #pragma unroll
;             for (int j = 0; j < 4; ++j) { v[q][j] = v[q][j] - mean; s2 += (v[q][j].x * v[q][j].x + v[q][j].y * v[q][j].y) + (v[q][j].z * v[q][j].z + v[q][j].w * v[q][j].w); }
;             const float rstd = 1.f / sqrtf(wave_sum(s2) * (1.f / DM) + LN_EPS);
;             const f32x4* gp = (const f32x4*)(c.inp(IN_LNG) + (size_t)(l - 1) * DM) + lane; const f32x4* bp = (const f32x4*)(c.inp(IN_LNB) + (size_t)(l - 1) * DM) + lane;
;             f32x4* orow = (f32x4*)(c.out + (size_t)m * DM) + lane;
; #pragma unroll
;             for (int j = 0; j < 4; ++j) { v[q][j] = v[q][j] * rstd * gp[64 * j] + bp[64 * j]; if (l == NLAYER) orow[64 * j] = v[q][j]; }
;             if (l < NLAYER && lane == 0) *(float2*)((float*)(c.ws + WS_STATS) + (size_t)m * 2) = make_float2(mean, rstd);
.LBB0_487:
	s_add_i32 s54, s46, s26
	s_ashr_i32 s47, s46, 31
	s_min_i32 s16, s54, 0x7fff
	s_lshl_b64 s[60:61], s[46:47], 12
	s_ashr_i32 s17, s16, 31
	s_waitcnt vmcnt(0)
	v_lshl_add_u64 v[138:139], v[174:175], 0, s[60:61]
	s_lshl_b64 s[16:17], s[16:17], 12
	global_load_dwordx4 v[166:169], v[138:139], off nt
	global_load_dwordx4 v[162:165], v[138:139], off offset:1024 nt
	global_load_dwordx4 v[158:161], v[138:139], off offset:2048 nt
	global_load_dwordx4 v[154:157], v[138:139], off offset:3072 nt
	v_lshl_add_u64 v[138:139], v[174:175], 0, s[16:17]
	global_load_dwordx4 v[150:153], v[138:139], off nt
	global_load_dwordx4 v[146:149], v[138:139], off offset:1024 nt
	global_load_dwordx4 v[142:145], v[138:139], off offset:2048 nt
	s_nop 0
	global_load_dwordx4 v[138:141], v[138:139], off offset:3072 nt
	v_cndmask_b32_e64 v96, 0, 1, s[48:49]
	v_cmp_ne_u32_e64 s[42:43], 1, v96
	s_andn2_b64 vcc, exec, s[48:49]
	s_cbranch_vccnz .LBB0_500
	s_waitcnt vmcnt(0)
	v_mov_b32_e32 v170, v167
	v_mov_b32_e32 v171, v168
	v_mov_b32_e32 v172, v166
	v_mov_b32_e32 v173, v169
	v_pk_add_f32 v[170:171], v[170:171], v[172:173]
	v_mov_b32_e32 v172, v163
	v_mov_b32_e32 v173, v164
	v_mov_b32_e32 v180, v162
	v_mov_b32_e32 v181, v165
	v_pk_add_f32 v[172:173], v[172:173], v[180:181]
	v_add_f32_e32 v96, v170, v171
	v_pk_add_f32 v[172:173], v[172:173], v[172:173] op_sel:[0,1] op_sel_hi:[1,0]
	v_add_f32_e32 v170, 0, v96
	v_add_f32_e32 v180, v158, v159
	v_add_f32_e32 v182, v160, v161
	v_mov_b32_e32 v171, v154
	v_mov_b32_e32 v173, v155
	v_mov_b32_e32 v181, v156
	v_mov_b32_e32 v183, v157
	v_pk_add_f32 v[170:171], v[170:171], v[172:173]
	v_pk_add_f32 v[172:173], v[180:181], v[182:183]
	s_load_dwordx4 s[64:67], s[12:13], 0x98
	v_pk_add_f32 v[170:171], v[170:171], v[172:173]
	v_lshl_add_u64 v[184:185], v[178:179], 0, s[60:61]
	v_add_f32_e32 v96, v170, v171
	s_nop 1
	v_add_f32_dpp v96, v96, v96 quad_perm:[1,0,3,2] row_mask:0xf bank_mask:0xf bound_ctrl:1
	s_nop 1
	v_add_f32_dpp v96, v96, v96 quad_perm:[2,3,0,1] row_mask:0xf bank_mask:0xf bound_ctrl:1
	s_nop 1
	v_add_f32_dpp v96, v96, v96 row_half_mirror row_mask:0xf bank_mask:0xf bound_ctrl:1
	s_nop 1
	v_add_f32_dpp v96, v96, v96 row_mirror row_mask:0xf bank_mask:0xf bound_ctrl:1
	s_nop 0
	v_readlane_b32 s0, v96, 16
	v_readlane_b32 s6, v96, 48
	v_readlane_b32 s16, v96, 0
	v_readlane_b32 s17, v96, 32
	v_mov_b32_e32 v170, s0
	v_mov_b32_e32 v171, s6
	v_pk_add_f32 v[170:171], s[16:17], v[170:171]
	s_nop 0
	v_add_f32_e32 v96, v170, v171
	v_fmamk_f32 v167, v96, 0xba800000, v167
	v_fmamk_f32 v166, v96, 0xba800000, v166
	v_fmamk_f32 v169, v96, 0xba800000, v169
	v_fmac_f32_e32 v168, 0xba800000, v96
	v_pk_mul_f32 v[170:171], v[168:169], v[168:169]
	v_pk_mul_f32 v[172:173], v[166:167], v[166:167]
	v_fmamk_f32 v183, v96, 0xba800000, v165
	v_pk_mov_b32 v[180:181], v[172:173], v[170:171] op_sel:[1,0]
	v_mov_b32_e32 v173, v171
	v_fmamk_f32 v182, v96, 0xba800000, v164
	v_fmamk_f32 v163, v96, 0xba800000, v163
	v_fmac_f32_e32 v162, 0xba800000, v96
	v_pk_add_f32 v[170:171], v[180:181], v[172:173]
	v_pk_mul_f32 v[164:165], v[182:183], v[182:183]
	v_pk_mul_f32 v[172:173], v[162:163], v[162:163]
	v_fmac_f32_e32 v158, 0xba800000, v96
	v_pk_mov_b32 v[180:181], v[172:173], v[164:165] op_sel:[1,0]
	v_mov_b32_e32 v173, v165
	v_pk_add_f32 v[164:165], v[180:181], v[172:173]
	v_fmamk_f32 v160, v96, 0xba800000, v160
	v_pk_add_f32 v[164:165], v[164:165], v[164:165] op_sel_hi:[0,1]
	v_fmamk_f32 v159, v96, 0xba800000, v159
	v_mul_f32_e32 v164, v158, v158
	v_fmamk_f32 v161, v96, 0xba800000, v161
	v_pk_fma_f32 v[172:173], v[158:159], v[158:159], v[164:165] op_sel_hi:[1,1,0]
	v_mul_f32_e32 v164, v160, v160
	v_pk_add_f32 v[170:171], v[170:171], v[170:171] op_sel_hi:[0,1]
	v_pk_fma_f32 v[180:181], v[160:161], v[160:161], v[164:165] op_sel_hi:[1,1,0]
	v_fmamk_f32 v157, v96, 0xba800000, v157
	v_fmamk_f32 v156, v96, 0xba800000, v156
	v_fmamk_f32 v155, v96, 0xba800000, v155
	v_fmac_f32_e32 v154, 0xba800000, v96
	v_mul_f32_e32 v172, v154, v154
	v_mul_f32_e32 v180, v155, v155
	v_mul_f32_e32 v170, v156, v156
	v_mul_f32_e32 v164, v157, v157
	v_pk_add_f32 v[172:173], v[172:173], v[180:181]
	v_pk_add_f32 v[164:165], v[170:171], v[164:165]
	s_nop 0
	v_pk_add_f32 v[164:165], v[172:173], v[164:165]
	s_nop 0
	v_add_f32_e32 v164, v164, v165
	s_nop 1
	v_add_f32_dpp v164, v164, v164 quad_perm:[1,0,3,2] row_mask:0xf bank_mask:0xf bound_ctrl:1
	s_nop 1
	v_add_f32_dpp v164, v164, v164 quad_perm:[2,3,0,1] row_mask:0xf bank_mask:0xf bound_ctrl:1
	s_nop 1
	v_add_f32_dpp v164, v164, v164 row_half_mirror row_mask:0xf bank_mask:0xf bound_ctrl:1
	s_nop 1
	v_add_f32_dpp v164, v164, v164 row_mirror row_mask:0xf bank_mask:0xf bound_ctrl:1
	s_nop 0
	v_readlane_b32 s0, v164, 16
	v_readlane_b32 s6, v164, 48
	v_readlane_b32 s16, v164, 0
	v_readlane_b32 s17, v164, 32
	v_mov_b32_e32 v164, s0
	v_mov_b32_e32 v165, s6
	v_pk_add_f32 v[164:165], s[16:17], v[164:165]
	s_nop 0
	v_add_f32_e32 v164, v164, v165
	v_fmamk_f32 v164, v164, 0x3a800000, v219
	v_cmp_gt_f32_e32 vcc, s87, v164
	v_mul_f32_e32 v165, 0x4f800000, v164
	s_nop 0
	v_cndmask_b32_e32 v164, v164, v165, vcc
	v_sqrt_f32_e32 v165, v164
	s_nop 0
	v_add_u32_e32 v170, -1, v165
	v_fma_f32 v171, -v170, v165, v164
	v_cmp_ge_f32_e64 s[40:41], 0, v171
	v_add_u32_e32 v171, 1, v165
	s_nop 0
	v_cndmask_b32_e64 v170, v165, v170, s[40:41]
	v_fma_f32 v165, -v171, v165, v164
	v_cmp_lt_f32_e64 s[40:41], 0, v165
	s_nop 1
	v_cndmask_b32_e64 v165, v170, v171, s[40:41]
	v_mul_f32_e32 v170, 0x37800000, v165
	v_cndmask_b32_e32 v165, v165, v170, vcc
	v_cmp_class_f32_e32 vcc, v164, v213
	s_nop 1
	v_cndmask_b32_e32 v164, v165, v164, vcc
	v_div_scale_f32 v165, s[16:17], v164, v164, 1.0
	v_rcp_f32_e32 v170, v165
	s_lshl_b64 s[16:17], s[22:23], 2
	s_waitcnt lgkmcnt(0)
	s_add_u32 s20, s64, s16
	s_addc_u32 s21, s65, s17
	v_fma_f32 v171, -v165, v170, 1.0
	v_fmac_f32_e32 v170, v171, v170
	v_div_scale_f32 v171, vcc, 1.0, v164, 1.0
	v_mul_f32_e32 v172, v171, v170
	v_fma_f32 v173, -v165, v172, v171
	v_fmac_f32_e32 v172, v173, v170
	v_fma_f32 v165, -v165, v172, v171
	v_div_fmas_f32 v165, v165, v170, v172
	v_div_fixup_f32 v180, v165, v164, 1.0
	v_lshlrev_b64 v[164:165], 4, v[200:201]
	s_add_u32 s16, s66, s16
	v_lshl_add_u64 v[186:187], s[20:21], 0, v[164:165]
	s_addc_u32 s17, s67, s17
	v_lshl_add_u64 v[188:189], s[16:17], 0, v[164:165]
	v_pk_mul_f32 v[190:191], v[166:167], v[180:181] op_sel_hi:[1,0]
	global_load_dwordx4 v[164:167], v[186:187], off
	global_load_dwordx4 v[170:173], v[188:189], off
	v_pk_mul_f32 v[168:169], v[168:169], v[180:181] op_sel_hi:[1,0]
	s_andn2_b64 vcc, exec, s[50:51]
	s_waitcnt vmcnt(0)
	v_pk_fma_f32 v[168:169], v[166:167], v[168:169], v[172:173]
	v_pk_fma_f32 v[166:167], v[164:165], v[190:191], v[170:171]
	v_cndmask_b32_e64 v164, 0, 1, s[50:51]
	v_cmp_ne_u32_e64 s[40:41], 1, v164
	s_cbranch_vccnz .LBB0_490
	global_store_dwordx4 v[184:185], v[166:169], off
